# 4-workgroup group barrier (WGs sharing row panels, same XCD) instead of the grid barrier on 15 GEMM-to-GEMM seams
# speedup vs baseline: 1.0127x; 1.0020x over previous
_Z6mk_fwd4Args:
	v_and_b32_e32 v194, 0x3ff, v0
	v_mov_b32_e32 v1, v194
	s_mov_b32 s45, s2
	s_mov_b64 s[56:57], s[0:1]
	s_mov_b32 s100, 0
	s_nop 0
	v_cmp_gt_i32_e32 vcc, 32, v1
	s_and_saveexec_b64 s[4:5], vcc
	v_lshl_add_u32 v1, v1, 2, 0
	v_add_u32_e32 v1, 0x20140, v1
	v_mov_b32_e32 v2, 0
	ds_write_b32 v1, v2
	s_or_b64 exec, exec, s[4:5]
	s_waitcnt lgkmcnt(0)
	s_barrier
	s_getreg_b32 s0, hwreg(HW_REG_XCC_ID, 0, 4)
	s_mov_b32 s21, 0
	v_cmp_eq_u32_e64 s[2:3], 0, v194
	s_mov_b64 s[4:5], exec
	s_nop 0
	v_writelane_b32 v254, s2, 0
	s_nop 1
	v_writelane_b32 v254, s3, 1
	s_and_b64 s[2:3], s[4:5], s[2:3]
	s_mov_b64 exec, s[2:3]
	s_cbranch_execz .LBB0_5
	s_mov_b64 s[6:7], exec
	v_mbcnt_lo_u32_b32 v1, s6, 0
	v_mbcnt_hi_u32_b32 v1, s7, v1
	v_cmp_eq_u32_e32 vcc, 0, v1
	s_and_b64 s[2:3], exec, vcc
	s_mov_b64 exec, s[2:3]
	s_cbranch_execz .LBB0_5
	s_load_dwordx2 s[2:3], s[56:57], 0x80
	s_lshl_b32 s0, s0, 8
	s_and_b32 s0, s0, 0xf00
	v_mov_b32_e32 v1, 0x1d400000
	s_waitcnt lgkmcnt(0)
	s_add_u32 s0, s2, s0
	s_addc_u32 s1, s3, 0
	s_bcnt1_i32_b64 s2, s[6:7]
	v_mov_b32_e32 v2, s2
	global_atomic_add v1, v2, s[0:1] offset:1024

.LBB0_413:
	s_mov_b64 s[8:9], s[56:57]
	s_load_dword s1, s[8:9], 0x8c
	s_add_i32 s0, s91, 1
	s_mov_b64 s[6:7], -1
	s_waitcnt lgkmcnt(0)
	s_cmp_ge_i32 s0, s1
	s_cbranch_scc1 .LBB0_9
	s_cmp_lg_u32 s91, 0
	s_cbranch_scc0 .LBB0_468
	s_cmp_eq_u32 s91, 32
	s_cbranch_scc1 .Lgb_full
	s_add_i32 s1, s91, -1
	s_and_b32 s1, s1, 7
	s_movk_i32 s2, 0xe1
	s_bitcmp1_b32 s2, s1
	s_cbranch_scc1 .Lgb_start
.Lgb_full:
	s_getreg_b32 s1, hwreg(HW_REG_XCC_ID, 0, 4)
	s_waitcnt vmcnt(0)
	s_waitcnt vmcnt(0)
	s_barrier
	s_mov_b64 s[6:7], exec
	v_readlane_b32 s4, v254, 0
	v_readlane_b32 s5, v254, 1
	s_and_b64 s[4:5], s[6:7], s[4:5]
	s_mov_b64 exec, s[4:5]
	s_cbranch_execz .LBB0_467
	v_readlane_b32 s2, v254, 43
	s_load_dwordx2 s[8:9], s[8:9], 0x80
	s_waitcnt vmcnt(0) expcnt(0) lgkmcnt(0)
	v_mov_b32_e32 v0, s2
	ds_read_b32 v2, v0
	v_readlane_b32 s2, v254, 44
	s_and_b32 s1, s1, 15
	s_waitcnt lgkmcnt(0)
	v_cmp_ne_u32_e32 vcc, 0, v2
	v_mov_b32_e32 v0, s2
	ds_read_b32 v0, v0
	s_cbranch_vccnz .LBB0_431
	s_add_u32 s12, s8, 0x1d400200
	s_addc_u32 s13, s9, 0
	s_add_u32 s14, s8, 0x1d400400
	s_addc_u32 s15, s9, 0
	s_add_u32 s16, s8, 0x1d400500
	s_addc_u32 s17, s9, 0
	s_add_u32 s18, s8, 0x1d400600
	s_addc_u32 s19, s9, 0
	s_add_u32 s64, s8, 0x1d400700
	s_addc_u32 s65, s9, 0
	s_add_u32 s66, s8, 0x1d400800
	s_addc_u32 s67, s9, 0
	s_add_u32 s68, s8, 0x1d400900
	s_addc_u32 s69, s9, 0
	s_add_u32 s70, s8, 0x1d400a00
	s_addc_u32 s71, s9, 0
	s_add_u32 s72, s8, 0x1d400b00
	s_addc_u32 s73, s9, 0
	s_add_u32 s74, s8, 0x1d400c00
	s_addc_u32 s75, s9, 0
	s_add_u32 s76, s8, 0x1d400d00
	s_addc_u32 s77, s9, 0
	s_add_u32 s78, s8, 0x1d400e00
	s_addc_u32 s79, s9, 0
	s_load_dwordx2 s[4:5], s[80:81], 0x4
	s_add_u32 s80, s8, 0x1d400f00
	s_addc_u32 s81, s9, 0
	s_add_u32 s82, s8, 0x1d401000
	s_addc_u32 s83, s9, 0
	s_add_u32 s84, s8, 0x1d401100
	s_addc_u32 s85, s9, 0
	s_add_u32 s86, s8, 0x1d401200
	v_readlane_b32 s2, v254, 59
	s_addc_u32 s87, s9, 0
	s_waitcnt lgkmcnt(0)
	s_mul_i32 s2, s4, s2
	s_add_u32 s88, s8, 0x1d401300
	s_mul_i32 s2, s2, s5
	s_addc_u32 s89, s9, 0
	s_mov_b32 s4, 1
	s_branch .LBB0_419

.Lgb_start:
	s_waitcnt vmcnt(0)
	s_barrier
	s_mov_b64 s[6:7], exec
	v_readlane_b32 s4, v254, 0
	v_readlane_b32 s5, v254, 1
	s_add_u32 s100, s100, 4
	s_and_b64 s[4:5], s[6:7], s[4:5]
	s_mov_b64 exec, s[4:5]
	s_cbranch_execz .Lgb_join
	s_load_dwordx2 s[8:9], s[56:57], 0x80
	s_and_b32 s1, s45, 63
	s_lshl_b32 s1, s1, 8
	s_add_u32 s1, s1, 0x1d404000
	v_mov_b32_e32 v0, 1
	s_mov_b32 s2, 0
	s_waitcnt lgkmcnt(0)
	s_add_u32 s8, s8, s1
	s_addc_u32 s9, s9, 0
	global_atomic_add v99, v0, s[8:9]
	buffer_inv sc1
.Lgb_poll:
	global_load_dword v0, v99, s[8:9] sc1
	s_add_u32 s2, s2, 1
	s_waitcnt vmcnt(0)
	v_readfirstlane_b32 s1, v0
	s_nop 3
	s_cmp_ge_u32 s1, s100
	s_cbranch_scc1 .Lgb_done
	s_cmp_gt_u32 s2, 0x100000
	s_cbranch_scc1 .Lgb_done
	s_sleep 1
	s_branch .Lgb_poll

.Lgb_join:
	s_or_b64 exec, exec, s[6:7]
	s_barrier
	s_branch .LBB0_8

	.amdhsa_kernel _Z6mk_fwd4Args
		.amdhsa_group_segment_fixed_size 0
		.amdhsa_private_segment_fixed_size 0
		.amdhsa_kernarg_size 400
		.amdhsa_user_sgpr_count 2
		.amdhsa_user_sgpr_dispatch_ptr 0
		.amdhsa_user_sgpr_queue_ptr 0
		.amdhsa_user_sgpr_kernarg_segment_ptr 1
		.amdhsa_user_sgpr_dispatch_id 0
		.amdhsa_user_sgpr_kernarg_preload_length 0
		.amdhsa_user_sgpr_kernarg_preload_offset 0
		.amdhsa_user_sgpr_private_segment_size 0
		.amdhsa_uses_dynamic_stack 0
		.amdhsa_enable_private_segment 0
		.amdhsa_system_sgpr_workgroup_id_x 1
		.amdhsa_system_sgpr_workgroup_id_y 0
		.amdhsa_system_sgpr_workgroup_id_z 0
		.amdhsa_system_sgpr_workgroup_info 0
		.amdhsa_system_vgpr_workitem_id 2
		.amdhsa_next_free_vgpr 256
		.amdhsa_next_free_sgpr 102
		.amdhsa_accum_offset 256
		.amdhsa_reserve_vcc 1
		.amdhsa_float_round_mode_32 0
		.amdhsa_float_round_mode_16_64 0
		.amdhsa_float_denorm_mode_32 3
		.amdhsa_float_denorm_mode_16_64 3
		.amdhsa_dx10_clamp 1
		.amdhsa_ieee_mode 1
		.amdhsa_fp16_overflow 0
		.amdhsa_tg_split 0
		.amdhsa_exception_fp_ieee_invalid_op 0
		.amdhsa_exception_fp_denorm_src 0
		.amdhsa_exception_fp_ieee_div_zero 0
		.amdhsa_exception_fp_ieee_overflow 0
		.amdhsa_exception_fp_ieee_underflow 0
		.amdhsa_exception_fp_ieee_inexact 0
		.amdhsa_exception_int_div_zero 0
	.end_amdhsa_kernel

amdhsa.kernels:
  - .agpr_count:     0
    .args:
      - .offset:         0
        .size:           144
        .value_kind:     by_value
      - .offset:         144
        .size:           4
        .value_kind:     hidden_block_count_x
      - .offset:         148
        .size:           4
        .value_kind:     hidden_block_count_y
      - .offset:         152
        .size:           4
        .value_kind:     hidden_block_count_z
      - .offset:         156
        .size:           2
        .value_kind:     hidden_group_size_x
      - .offset:         158
        .size:           2
        .value_kind:     hidden_group_size_y
      - .offset:         160
        .size:           2
        .value_kind:     hidden_group_size_z
      - .offset:         162
        .size:           2
        .value_kind:     hidden_remainder_x
      - .offset:         164
        .size:           2
        .value_kind:     hidden_remainder_y
      - .offset:         166
        .size:           2
        .value_kind:     hidden_remainder_z
      - .offset:         184
        .size:           8
        .value_kind:     hidden_global_offset_x
      - .offset:         192
        .size:           8
        .value_kind:     hidden_global_offset_y
      - .offset:         200
        .size:           8
        .value_kind:     hidden_global_offset_z
      - .offset:         208
        .size:           2
        .value_kind:     hidden_grid_dims
      - .offset:         232
        .size:           8
        .value_kind:     hidden_multigrid_sync_arg
      - .offset:         264
        .size:           4
        .value_kind:     hidden_dynamic_lds_size
    .group_segment_fixed_size: 0
    .kernarg_segment_align: 8
    .kernarg_segment_size: 400
    .language:       OpenCL C
    .language_version:
      - 2
      - 0
    .max_flat_workgroup_size: 512
    .name:           _Z6mk_fwd4Args
    .private_segment_fixed_size: 0
    .sgpr_count:     108
    .sgpr_spill_count: 90
    .symbol:         _Z6mk_fwd4Args.kd
    .uniform_work_group_size: 1
    .uses_dynamic_stack: false
    .vgpr_count:     256
    .vgpr_spill_count: 0
    .wavefront_size: 64
